# v100 + attention tile head: next-tile DMA piece computes m0 directly ahead of the exit test (no m0 save/restore, no s_nop)
# speedup vs baseline: 1.0089x; 1.0028x over previous
; #define ATT_STAGE(t, buf) do { _Pragma("unroll") for (int i_ = 0; i_ < 2; ++i_) { \
;         glds16(Kt + (size_t)(t) * 131072, ksrc[i_], (unsigned)__builtin_amdgcn_readfirstlane(ldsb + KBUF + (buf) * 16384 + (w * 2 + i_) * 1024)); \
;         glds16(Vt + (size_t)(t) * 131072, vsrc[i_], (unsigned)__builtin_amdgcn_readfirstlane(ldsb + VBUF + (buf) * 16384 + (w * 2 + i_) * 1024)); } } while (0)
; __device__ __forceinline__ void attn_unit(ATT_LAS unsigned char* lds, const bf16_t* Qg, const bf16_t* Kg, const bf16_t* Vg, bf16_t* Og, int b, int head, int qb, float lam, const float* subg) {
;     ...
;     for (int t = 0; t < NT; ++t) {
;         const int buf = t & 1;
;         if (t + 1 < NT) ATT_STAGE(t + 1, buf ^ 1);
.LBB0_289:
	s_and_b32 s4, s79, 1
	s_add_i32 s79, s79, 1
	s_lshl_b32 s5, s4, 14
	s_xor_b32 s5, s5, 0x4000
	s_add_i32 m0, s5, s77
	s_cmp_ge_u32 s79, s76
	s_cbranch_scc1 .Lq_prefetch
	global_load_lds_dwordx4 v198, s[92:93]
